# attention softmax: exp in place, max subtraction and row sums as packed f32 adds with two accumulator pairs folded into lsum at loop exit
# baseline (speedup 1.0000x reference)
; DEV int ltid() { int t = threadIdx.x; asm volatile("" : "+v"(t)); return t; }
; DEV void attn_tile(const Params& p, int l, int tile, char* smem, bool do_store = true) {
;     ...
;   if (tile < 1024) { b = tile >> 7; head = (tile >> 5) & 3; q0 = (tile & 31) * 128; nkeys = TK; qbase = b * SEQ; }
;   else { const int tt = tile - 1024; b = tt >> 3; head = (tt >> 1) & 3; q0 = (tt & 1) * 128; nkeys = CTXL; qbase = T_LAT + b * CTXL; }
;   const int tid = ltid(), lane = tid & 63, w = tid >> 6, ql = lane & 31, hh = lane >> 5, map = w >> 2, qg = w & 3;
;   const int qrow = qbase + q0 + qg * 32 + ql;
;   const float lam_init = l == 0 ? 0.2f : 0.35550907f;
;   float lam;
;   {
;     const float a1 = p.att_lq1[l * 64 + lane] * p.att_lk1[l * 64 + lane];
;     const float a2 = p.att_lq2[l * 64 + lane] * p.att_lk2[l * 64 + lane];
;     lam = __expf(wsum(a1)) - __expf(wsum(a2)) + lam_init;
;   }
;   bf16x8 qf[4];
; #pragma unroll
;   for (int s = 0; s < 4; ++s) qf[s] = *(const bf16x8*)(ZQ + (size_t)qrow * 512 + head * 128 + map * 64 + s * 16 + hh * 8);
;   f32x16 o[4];
; #pragma unroll
;   for (int dt = 0; dt < 4; ++dt)
; #pragma unroll
;     for (int e = 0; e < 16; ++e) o[dt][e] = 0.f;
;   float m = -1e30f, lsum = 0.f;
;   const int kr0 = tid >> 4, kch = tid & 15;
;   const int vr0 = tid >> 4, vch = tid & 15;
;   const bf16_t* vtb = VT + ((size_t)((b * 4 + head) * 128)) * TK;
;   u32x4 kreg[4], vreg[4];
;   auto gload = [&](int kt) {
;     const int k0 = kt * 128;
; #pragma unroll
;     for (int i = 0; i < 4; ++i) {
;       const int kidx = k0 + kr0 + 32 * i;
;       const int krow = kidx < CTXL ? T_LAT + b * CTXL + kidx : b * SEQ + kidx - CTXL;
;       kreg[i] = *(const u32x4*)(ZK + (size_t)krow * 512 + head * 128 + kch * 8);
;       vreg[i] = *(const u32x4*)(vtb + (size_t)(vr0 + 32 * i) * TK + k0 + vch * 8);
;     }
;   };
;   auto lstore = [&](int st) {
;     char* Ks = smem + st * ATT2_ST;
;     char* Vs = Ks + 128 * KROW;
; #pragma unroll
;     for (int i = 0; i < 4; ++i) {
;       *(u32x4*)(Ks + (kr0 + 32 * i) * KROW + kch * 16) = kreg[i];
;       *(u32x4*)(Vs + (vr0 + 32 * i) * KROW + vch * 16) = vreg[i];
;     }
;   };
;   const int nkt = nkeys >> 7;
;   gload(0);
;   __syncthreads();
;   lstore(0);
;   __syncthreads();
.LBB0_598:
	v_mov_b32_e32 v192, v226
	v_readlane_b32 s56, v254, 58
	v_readlane_b32 s57, v254, 59
	v_and_or_b32 v2, v192, 63, s96
	v_readlane_b32 s58, v254, 60
	v_readlane_b32 s59, v254, 61
	v_readlane_b32 s60, v254, 62
	v_readlane_b32 s61, v254, 63
	v_readlane_b32 s62, v255, 0
	v_readlane_b32 s63, v255, 1
	v_readlane_b32 s64, v255, 2
	v_readlane_b32 s65, v255, 3
	v_readlane_b32 s66, v255, 4
	v_readlane_b32 s67, v255, 5
	v_ashrrev_i32_e32 v3, 31, v2
	v_readlane_b32 s68, v255, 6
	v_readlane_b32 s69, v255, 7
	v_readlane_b32 s70, v255, 8
	v_readlane_b32 s71, v255, 9
	s_mov_b64 s[56:57], s[60:61]
	v_lshlrev_b64 v[2:3], 2, v[2:3]
	s_mov_b64 s[58:59], s[62:63]
	s_mov_b64 s[60:61], s[64:65]
	s_mov_b64 s[62:63], s[66:67]
	s_mov_b64 s[64:65], s[68:69]
	s_mov_b64 s[66:67], s[70:71]
	v_lshl_add_u64 v[4:5], s[64:65], 0, v[2:3]
	global_load_dword v1, v[4:5], off
	v_lshl_add_u64 v[4:5], s[66:67], 0, v[2:3]
	global_load_dword v6, v[4:5], off
	v_readlane_b32 s56, v251, 21
	v_readlane_b32 s57, v251, 22
	v_readlane_b32 s58, v251, 23
	v_readlane_b32 s59, v251, 24
	v_lshl_add_u64 v[4:5], s[56:57], 0, v[2:3]
	global_load_dword v4, v[4:5], off
	v_lshl_add_u64 v[2:3], s[58:59], 0, v[2:3]
	global_load_dword v2, v[2:3], off
	v_bfe_u32 v193, v192, 6, 2
	v_and_b32_e32 v194, 31, v192
	s_add_i32 s0, s38, s39
	v_lshlrev_b32_e32 v0, 5, v193
	v_add3_u32 v0, s0, v194, v0
	v_readlane_b32 s0, v252, 19
	v_readlane_b32 s1, v252, 20
	v_ashrrev_i32_e32 v195, 8, v192
	v_bfe_u32 v190, v192, 5, 1
	v_lshlrev_b32_e32 v96, 4, v190
	v_ashrrev_i32_e32 v200, 4, v192
	v_readlane_b32 s64, v251, 29
	v_readlane_b32 s65, v251, 30
	v_readlane_b32 s64, v255, 38
	v_readlane_b32 s52, v252, 21
	v_add_u32_e32 v14, 32, v200
	v_readlane_b32 s65, v255, 39
	v_readlane_b32 s53, v252, 22
	v_add_u32_e32 v22, 64, v200
	s_movk_i32 s41, 0x2200
	v_add_u32_e32 v32, 0x60, v200
	v_readlane_b32 s60, v251, 25
	v_readlane_b32 s61, v251, 26
	v_readlane_b32 s66, v251, 31
	v_readlane_b32 s67, v251, 32
	v_readlane_b32 s68, v251, 33
	v_readlane_b32 s69, v251, 34
	v_readlane_b32 s70, v251, 35
	v_readlane_b32 s71, v251, 36
	v_readlane_b32 s60, v255, 32
	v_readlane_b32 s66, v255, 34
	v_readlane_b32 s68, v255, 36
	v_lshrrev_b32_e32 v191, 6, v192
	v_lshl_or_b32 v204, v195, 7, v96
	v_mul_u32_u24_e32 v201, 0x110, v194
	v_mov_b32_e32 v209, 0
	v_mov_b32_e32 v208, 0xf149f2ca
	v_mov_b32_e32 v244, 0
	v_mov_b32_e32 v245, 0
	v_mov_b32_e32 v246, 0
	v_mov_b32_e32 v247, 0
	v_readlane_b32 s61, v255, 33
	v_readlane_b32 s67, v255, 35
	v_readlane_b32 s69, v255, 37
	v_readlane_b32 s70, v255, 41
	s_mov_b32 s71, 0x8000
	v_readlane_b32 s62, v251, 27
	v_readlane_b32 s63, v251, 28
	s_waitcnt vmcnt(2)
	v_mul_f32_e32 v7, v1, v6
	s_nop 1
	v_mov_b32_dpp v5, v7 quad_perm:[1,0,3,2] row_mask:0xf bank_mask:0xf bound_ctrl:1
	v_fmac_f32_e32 v5, v1, v6
	s_waitcnt vmcnt(0)
	v_mul_f32_e32 v3, v4, v2
	v_add_f32_dpp v1, v5, v5 quad_perm:[2,3,0,1] row_mask:0xf bank_mask:0xf bound_ctrl:1
	s_nop 1
	v_add_f32_dpp v1, v1, v1 row_half_mirror row_mask:0xf bank_mask:0xf bound_ctrl:1
	s_nop 1
	v_add_f32_dpp v1, v1, v1 row_mirror row_mask:0xf bank_mask:0xf bound_ctrl:1
	v_mov_b32_e32 v5, v1
	s_nop 1
	v_permlane16_swap_b32_e32 v1, v5
	v_add_f32_e32 v196, v1, v5
	s_nop 0
	v_mov_b32_dpp v1, v3 quad_perm:[1,0,3,2] row_mask:0xf bank_mask:0xf bound_ctrl:1
	v_fmac_f32_e32 v1, v4, v2
	v_mov_b32_e32 v5, v97
	v_mov_b32_e32 v197, v196
	v_add_f32_dpp v1, v1, v1 quad_perm:[2,3,0,1] row_mask:0xf bank_mask:0xf bound_ctrl:1
	s_nop 0
	v_permlane32_swap_b32_e32 v196, v197
	v_add_f32_dpp v1, v1, v1 row_half_mirror row_mask:0xf bank_mask:0xf bound_ctrl:1
	s_nop 1
	v_add_f32_dpp v1, v1, v1 row_mirror row_mask:0xf bank_mask:0xf bound_ctrl:1
	v_mov_b32_e32 v2, v1
	s_nop 1
	v_permlane16_swap_b32_e32 v1, v2
	v_add_f32_e32 v198, v1, v2
	v_ashrrev_i32_e32 v1, 31, v0
	v_lshlrev_b64 v[0:1], 10, v[0:1]
	v_lshl_add_u64 v[0:1], s[0:1], 0, v[0:1]
	s_lshl_b32 s0, s37, 7
	s_and_b32 s0, s0, 0x180
	s_lshl_b32 s54, s0, 1
	v_lshl_add_u64 v[182:183], v[0:1], 0, s[54:55]
	v_lshlrev_b32_e32 v0, 6, v195
	v_ashrrev_i32_e32 v1, 31, v0
	v_lshl_add_u64 v[0:1], v[0:1], 1, v[182:183]
	s_movk_i32 s37, 0x100
	v_lshl_add_u64 v[0:1], v[0:1], 0, v[96:97]
	v_cmp_gt_i32_e32 vcc, s37, v200
	global_load_dwordx4 v[110:113], v[0:1], off
	global_load_dwordx4 v[106:109], v[0:1], off offset:32
	global_load_dwordx4 v[102:105], v[0:1], off offset:64
	global_load_dwordx4 v[98:101], v[0:1], off offset:96
	v_cndmask_b32_e64 v0, 12, 8, vcc
	s_movk_i32 s37, 0xe0
	s_lshl_b32 s1, s30, 9
	v_cndmask_b32_e32 v1, v236, v237, vcc
	v_lshlrev_b32_e64 v0, v0, s30
	v_cmp_gt_i32_e32 vcc, s37, v200
	s_or_b32 s0, s0, s1
	v_add3_u32 v0, v1, v200, v0
	v_cndmask_b32_e64 v10, 12, 8, vcc
	s_movk_i32 s37, 0xc0
	s_mul_hi_i32 s1, s0, 0x2200
	s_mulk_i32 s0, 0x2200
	v_ashrrev_i32_e32 v1, 31, v0
	v_cndmask_b32_e32 v11, v236, v237, vcc
	v_lshlrev_b32_e64 v10, v10, s30
	v_cmp_gt_i32_e32 vcc, s37, v200
	s_add_u32 s38, s64, s0
	v_lshlrev_b64 v[0:1], 10, v[0:1]
	v_add3_u32 v10, v11, v14, v10
	v_cndmask_b32_e64 v18, 12, 8, vcc
	s_movk_i32 s37, 0xa0
	s_addc_u32 s39, s65, s1
	v_lshl_add_u64 v[0:1], s[52:53], 0, v[0:1]
	v_lshlrev_b32_e32 v2, 4, v192
	v_ashrrev_i32_e32 v11, 31, v10
	v_cndmask_b32_e32 v19, v236, v237, vcc
	v_lshlrev_b32_e64 v18, v18, s30
	v_cmp_gt_i32_e32 vcc, s37, v200
	v_lshl_add_u64 v[0:1], v[0:1], 0, s[54:55]
	v_and_b32_e32 v4, 0xf0, v2
	v_mov_b64_e32 v[30:31], s[38:39]
	v_lshlrev_b64 v[10:11], 10, v[10:11]
	v_add3_u32 v18, v19, v22, v18
	v_cndmask_b32_e64 v26, 12, 8, vcc
	v_lshl_add_u64 v[0:1], v[0:1], 0, v[4:5]
	v_mad_i64_i32 v[6:7], s[38:39], v200, s41, v[30:31]
	v_lshl_add_u64 v[10:11], s[52:53], 0, v[10:11]
	v_ashrrev_i32_e32 v19, 31, v18
	v_cndmask_b32_e32 v27, v236, v237, vcc
	v_lshlrev_b32_e64 v26, v26, s30
	global_load_dwordx4 v[0:3], v[0:1], off
	v_lshl_add_u64 v[6:7], v[6:7], 0, v[4:5]
	v_lshl_add_u64 v[10:11], v[10:11], 0, s[54:55]
	v_lshlrev_b64 v[18:19], 10, v[18:19]
	v_add3_u32 v26, v27, v32, v26
	global_load_dwordx4 v[6:9], v[6:7], off
	v_lshl_add_u64 v[10:11], v[10:11], 0, v[4:5]
	v_mad_i64_i32 v[14:15], s[38:39], v14, s41, v[30:31]
	v_lshl_add_u64 v[18:19], s[52:53], 0, v[18:19]
	v_ashrrev_i32_e32 v27, 31, v26
	global_load_dwordx4 v[10:13], v[10:11], off
	v_lshl_add_u64 v[14:15], v[14:15], 0, v[4:5]
	v_lshl_add_u64 v[18:19], v[18:19], 0, s[54:55]
	v_lshlrev_b64 v[26:27], 10, v[26:27]
	global_load_dwordx4 v[14:17], v[14:15], off
	v_lshl_add_u64 v[18:19], v[18:19], 0, v[4:5]
	v_mad_i64_i32 v[22:23], s[38:39], v22, s41, v[30:31]
	v_lshl_add_u64 v[26:27], s[52:53], 0, v[26:27]
	global_load_dwordx4 v[18:21], v[18:19], off
	v_lshl_add_u64 v[22:23], v[22:23], 0, v[4:5]
	v_lshl_add_u64 v[26:27], v[26:27], 0, s[54:55]
	global_load_dwordx4 v[22:25], v[22:23], off
	v_lshl_add_u64 v[26:27], v[26:27], 0, v[4:5]
	v_mad_i64_i32 v[30:31], s[38:39], v32, s41, v[30:31]
	global_load_dwordx4 v[26:29], v[26:27], off
	v_lshl_add_u64 v[30:31], v[30:31], 0, v[4:5]
	global_load_dwordx4 v[30:33], v[30:31], off
	s_movk_i32 s37, 0x110
	v_mul_lo_u32 v34, v200, s37
	v_add3_u32 v202, 0, v34, v4
	s_barrier
; DEV int key_of_slot(int x) { return (x & 0x13) | ((x & 8) >> 1) | ((x & 4) << 1); }
; DEV void attn_tile(const Params& p, int l, int tile, char* smem, bool do_store = true) {
;     ...
;   f32x16 o[4];
; #pragma unroll
;   for (int dt = 0; dt < 4; ++dt)
; #pragma unroll
;     for (int e = 0; e < 16; ++e) o[dt][e] = 0.f;
;   float m = -1e30f, lsum = 0.f;
;   const int kr0 = tid >> 4, kch = tid & 15;
;   const int vr0 = tid >> 4, vch = tid & 15;
;   const bf16_t* vtb = VT + ((size_t)((b * 4 + head) * 128)) * TK;
;   u32x4 kreg[4], vreg[4];
;   auto gload = [&](int kt) {
;     const int k0 = kt * 128;
; #pragma unroll
;     for (int i = 0; i < 4; ++i) {
;       const int kidx = k0 + kr0 + 32 * i;
;       const int krow = kidx < CTXL ? T_LAT + b * CTXL + kidx : b * SEQ + kidx - CTXL;
;       kreg[i] = *(const u32x4*)(ZK + (size_t)krow * 512 + head * 128 + kch * 8);
;       vreg[i] = *(const u32x4*)(vtb + (size_t)(vr0 + 32 * i) * TK + k0 + vch * 8);
;     }
;   };
;   auto lstore = [&](int st) {
;     char* Ks = smem + st * ATT2_ST;
;     char* Vs = Ks + 128 * KROW;
; #pragma unroll
;     for (int i = 0; i < 4; ++i) {
;       *(u32x4*)(Ks + (kr0 + 32 * i) * KROW + kch * 16) = kreg[i];
;       *(u32x4*)(Vs + (vr0 + 32 * i) * KROW + vch * 16) = vreg[i];
;     }
;   };
;   const int nkt = nkeys >> 7;
;   gload(0);
;   __syncthreads();
;   lstore(0);
;   __syncthreads();
;   const int kos = key_of_slot(ql);
	s_waitcnt vmcnt(7)
	ds_write_b128 v202, v[0:3]
	s_waitcnt vmcnt(6)
	ds_write_b128 v202, v[6:9] offset:34816
	s_waitcnt vmcnt(5)
	ds_write_b128 v202, v[10:13] offset:8704
	s_waitcnt vmcnt(4)
	ds_write_b128 v202, v[14:17] offset:43520
	s_waitcnt vmcnt(3)
	ds_write_b128 v202, v[18:21] offset:17408
	s_waitcnt vmcnt(2)
	ds_write_b128 v202, v[22:25] offset:52224
	s_waitcnt vmcnt(1)
	ds_write_b128 v202, v[26:29] offset:26112
	s_waitcnt vmcnt(0)
	ds_write_b128 v202, v[30:33] offset:60928
	v_lshrrev_b32_e32 v1, 1, v192
	v_lshlrev_b32_e32 v2, 1, v192
	v_and_b32_e32 v0, 19, v192
	v_and_b32_e32 v1, 4, v1
	v_and_b32_e32 v2, 8, v2
	v_or3_b32 v0, v1, v0, v2
	v_mul_u32_u24_e32 v203, 0x110, v0
	v_mov_b64_e32 v[0:1], s[0:1]
	v_mad_i64_i32 v[0:1], s[0:1], v200, s41, v[0:1]
	s_add_u32 s38, s52, s54
	v_readlane_b32 s0, v255, 11
	s_addc_u32 s39, s53, 0
	v_or_b32_e32 v0, v0, v4
	v_readlane_b32 s1, v255, 12
	v_mov_b32_e32 v14, v97
	v_mov_b32_e32 v15, v97
	v_mov_b32_e32 v199, v198
	v_lshl_add_u64 v[184:185], s[38:39], 0, v[4:5]
	s_lshl_b32 s36, s36, 7
	v_lshl_add_u64 v[186:187], s[0:1], 0, v[0:1]
	v_mov_b32_e32 v0, v97
	v_mov_b32_e32 v1, v97
	v_mov_b32_e32 v2, v97
	v_mov_b32_e32 v3, v97
	v_mov_b32_e32 v4, v97
	v_mov_b32_e32 v6, v97
	v_mov_b32_e32 v7, v97
	v_mov_b32_e32 v8, v97
	v_mov_b32_e32 v9, v97
	v_mov_b32_e32 v10, v97
	v_mov_b32_e32 v11, v97
	v_mov_b32_e32 v12, v97
	v_mov_b32_e32 v13, v97
	v_mov_b64_e32 v[30:31], v[14:15]
	v_mov_b64_e32 v[46:47], v[14:15]
	v_mov_b64_e32 v[62:63], v[14:15]
	v_permlane32_swap_b32_e32 v198, v199
	s_addk_i32 s36, 0x80
	v_mov_b64_e32 v[28:29], v[12:13]
	v_mov_b64_e32 v[26:27], v[10:11]
	v_mov_b64_e32 v[24:25], v[8:9]
	v_mov_b64_e32 v[22:23], v[6:7]
	v_mov_b64_e32 v[20:21], v[4:5]
	v_mov_b64_e32 v[18:19], v[2:3]
	v_mov_b64_e32 v[16:17], v[0:1]
	v_mov_b64_e32 v[44:45], v[12:13]
	v_mov_b64_e32 v[42:43], v[10:11]
	v_mov_b64_e32 v[40:41], v[8:9]
	v_mov_b64_e32 v[38:39], v[6:7]
	v_mov_b64_e32 v[36:37], v[4:5]
	v_mov_b64_e32 v[34:35], v[2:3]
	v_mov_b64_e32 v[32:33], v[0:1]
	v_mov_b64_e32 v[60:61], v[12:13]
	v_mov_b64_e32 v[58:59], v[10:11]
	v_mov_b64_e32 v[56:57], v[8:9]
	v_mov_b64_e32 v[54:55], v[6:7]
	v_mov_b64_e32 v[52:53], v[4:5]
	v_mov_b64_e32 v[50:51], v[2:3]
	v_mov_b64_e32 v[48:49], v[0:1]
	s_mov_b32 s0, 0
	s_movk_i32 s54, 0x4000
	s_movk_i32 s41, 0x600
	v_readfirstlane_b32 s101, v226
	s_waitcnt lgkmcnt(0)
	s_barrier
	s_lshr_b32 s101, s101, 8
	s_cmp_eq_u32 s101, 0
	s_cbranch_scc1 .Latt_noprio
	s_setprio 1

; DEV void attn_tile(const Params& p, int l, int tile, char* smem, bool do_store = true) {
;     ...
;     bf16x8 pb0[2], pb1[2];
;     {
;       float pe[16];
; #pragma unroll
;       for (int e = 0; e < 16; ++e) { pe[e] = __builtin_amdgcn_exp2f(s0[e] - m); lsum += pe[e]; }
; #pragma unroll
;       for (int k2 = 0; k2 < 2; ++k2) {
;         u32x4 u;
;         u[0] = pk2(pe[8 * k2 + 0], pe[8 * k2 + 1]); u[1] = pk2(pe[8 * k2 + 2], pe[8 * k2 + 3]);
;         u[2] = pk2(pe[8 * k2 + 4], pe[8 * k2 + 5]); u[3] = pk2(pe[8 * k2 + 6], pe[8 * k2 + 7]);
;         pb0[k2] = __builtin_bit_cast(bf16x8, u);
;       }
;     }
; #pragma unroll
;     for (int dt = 0; dt < 4; ++dt)
; #pragma unroll
;       for (int k2 = 0; k2 < 2; ++k2) o[dt] = __builtin_amdgcn_mfma_f32_32x32x16_bf16(vf[dt * 2 + k2], pb0[k2], o[dt], 0, 0, 0);
; #pragma unroll
;     for (int dt = 0; dt < 4; ++dt)
; #pragma unroll
;       for (int k2 = 0; k2 < 2; ++k2) vf[dt * 2 + k2] = *(const bf16x8*)(vp + dt * 32 * KROW + (32 + k2 * 16) * 2);
;     {
;       float pe[16];
; #pragma unroll
;       for (int e = 0; e < 16; ++e) { pe[e] = __builtin_amdgcn_exp2f(s1[e] - m); lsum += pe[e]; }
; #pragma unroll
;       for (int k2 = 0; k2 < 2; ++k2) {
;         u32x4 u;
;         u[0] = pk2(pe[8 * k2 + 0], pe[8 * k2 + 1]); u[1] = pk2(pe[8 * k2 + 2], pe[8 * k2 + 3]);
;         u[2] = pk2(pe[8 * k2 + 4], pe[8 * k2 + 5]); u[3] = pk2(pe[8 * k2 + 6], pe[8 * k2 + 7]);
;         pb1[k2] = __builtin_bit_cast(bf16x8, u);
;       }
;     }
; #pragma unroll
;     for (int dt = 0; dt < 4; ++dt)
; #pragma unroll
;       for (int k2 = 0; k2 < 2; ++k2) o[dt] = __builtin_amdgcn_mfma_f32_32x32x16_bf16(vf[dt * 2 + k2], pb1[k2], o[dt], 0, 0, 0);
.LBB0_599:
	v_pk_add_f32 v[80:81], v[80:81], v[208:209] op_sel_hi:[1,0] neg_lo:[0,1] neg_hi:[0,1]
	v_pk_add_f32 v[82:83], v[82:83], v[208:209] op_sel_hi:[1,0] neg_lo:[0,1] neg_hi:[0,1]
	v_pk_add_f32 v[84:85], v[84:85], v[208:209] op_sel_hi:[1,0] neg_lo:[0,1] neg_hi:[0,1]
	v_pk_add_f32 v[86:87], v[86:87], v[208:209] op_sel_hi:[1,0] neg_lo:[0,1] neg_hi:[0,1]
	v_pk_add_f32 v[88:89], v[88:89], v[208:209] op_sel_hi:[1,0] neg_lo:[0,1] neg_hi:[0,1]
	v_pk_add_f32 v[90:91], v[90:91], v[208:209] op_sel_hi:[1,0] neg_lo:[0,1] neg_hi:[0,1]
	v_pk_add_f32 v[92:93], v[92:93], v[208:209] op_sel_hi:[1,0] neg_lo:[0,1] neg_hi:[0,1]
	v_pk_add_f32 v[94:95], v[94:95], v[208:209] op_sel_hi:[1,0] neg_lo:[0,1] neg_hi:[0,1]
	v_exp_f32_e32 v80, v80
	v_exp_f32_e32 v81, v81
	v_exp_f32_e32 v82, v82
	v_exp_f32_e32 v83, v83
	v_exp_f32_e32 v84, v84
	v_exp_f32_e32 v85, v85
	v_exp_f32_e32 v86, v86
	v_exp_f32_e32 v87, v87
	v_exp_f32_e32 v88, v88
	v_exp_f32_e32 v89, v89
	v_exp_f32_e32 v90, v90
	v_exp_f32_e32 v91, v91
	v_exp_f32_e32 v92, v92
	v_exp_f32_e32 v93, v93
	v_exp_f32_e32 v94, v94
	v_exp_f32_e32 v95, v95
	v_pk_add_f32 v[244:245], v[80:81], v[244:245]
	v_pk_add_f32 v[246:247], v[82:83], v[246:247]
	v_cvt_pk_bf16_f32 v80, v80, v81
	v_cvt_pk_bf16_f32 v81, v82, v83
	v_cvt_pk_bf16_f32 v82, v84, v85
	v_cvt_pk_bf16_f32 v83, v86, v87
	v_pk_add_f32 v[244:245], v[84:85], v[244:245]
	v_pk_add_f32 v[246:247], v[86:87], v[246:247]
	s_waitcnt lgkmcnt(5)
	v_mfma_f32_32x32x16_bf16 v[32:47], v[166:169], v[80:83], v[32:47]
	v_cvt_pk_bf16_f32 v84, v88, v89
	v_cvt_pk_bf16_f32 v85, v90, v91
	v_cvt_pk_bf16_f32 v86, v92, v93
	v_cvt_pk_bf16_f32 v87, v94, v95
	v_pk_add_f32 v[244:245], v[88:89], v[244:245]
	v_pk_add_f32 v[246:247], v[90:91], v[246:247]
	v_mfma_f32_32x32x16_bf16 v[48:63], v[174:177], v[80:83], v[48:63]
	v_pk_add_f32 v[244:245], v[92:93], v[244:245]
	v_pk_add_f32 v[246:247], v[94:95], v[246:247]
	v_pk_add_f32 v[64:65], v[64:65], v[208:209] op_sel_hi:[1,0] neg_lo:[0,1] neg_hi:[0,1]
	v_pk_add_f32 v[66:67], v[66:67], v[208:209] op_sel_hi:[1,0] neg_lo:[0,1] neg_hi:[0,1]
	v_pk_add_f32 v[68:69], v[68:69], v[208:209] op_sel_hi:[1,0] neg_lo:[0,1] neg_hi:[0,1]
	v_pk_add_f32 v[70:71], v[70:71], v[208:209] op_sel_hi:[1,0] neg_lo:[0,1] neg_hi:[0,1]
	s_waitcnt lgkmcnt(3)
	v_mfma_f32_32x32x16_bf16 v[16:31], v[146:149], v[80:83], v[16:31]
	s_xor_b32 s1, s1, 1
	s_mul_i32 s1, s1, 0x11000
	s_addk_i32 s31, 0x80
	v_pk_add_f32 v[72:73], v[72:73], v[208:209] op_sel_hi:[1,0] neg_lo:[0,1] neg_hi:[0,1]
	v_pk_add_f32 v[74:75], v[74:75], v[208:209] op_sel_hi:[1,0] neg_lo:[0,1] neg_hi:[0,1]
	v_pk_add_f32 v[76:77], v[76:77], v[208:209] op_sel_hi:[1,0] neg_lo:[0,1] neg_hi:[0,1]
	v_pk_add_f32 v[78:79], v[78:79], v[208:209] op_sel_hi:[1,0] neg_lo:[0,1] neg_hi:[0,1]
	s_waitcnt lgkmcnt(1)
	v_mfma_f32_32x32x16_bf16 v[0:15], v[154:157], v[80:83], v[0:15]
	s_mov_b64 s[38:39], 0x100
	s_add_i32 s0, s0, 1
	v_lshl_add_u64 v[186:187], v[186:187], 0, s[38:39]
	s_cmp_eq_u32 s36, s31
	v_exp_f32_e32 v64, v64
	v_exp_f32_e32 v65, v65
	v_exp_f32_e32 v66, v66
	v_exp_f32_e32 v67, v67
	v_mfma_f32_32x32x16_bf16 v[32:47], v[162:165], v[84:87], v[32:47]
	v_exp_f32_e32 v68, v68
	v_exp_f32_e32 v69, v69
	v_exp_f32_e32 v70, v70
	v_exp_f32_e32 v71, v71
	v_mfma_f32_32x32x16_bf16 v[48:63], v[170:173], v[84:87], v[48:63]
	v_exp_f32_e32 v72, v72
	v_exp_f32_e32 v73, v73
	v_exp_f32_e32 v74, v74
	v_exp_f32_e32 v75, v75
	v_mfma_f32_32x32x16_bf16 v[16:31], v[150:153], v[84:87], v[16:31]
	v_exp_f32_e32 v76, v76
	v_exp_f32_e32 v77, v77
	v_exp_f32_e32 v78, v78
	v_exp_f32_e32 v79, v79
	s_waitcnt lgkmcnt(0)
	v_mfma_f32_32x32x16_bf16 v[0:15], v[158:161], v[84:87], v[0:15]
	ds_read_b128 v[150:153], v205 offset:35008
	ds_read_b128 v[154:157], v205 offset:35040
	ds_read_b128 v[158:161], v205 offset:43712
	ds_read_b128 v[146:149], v205 offset:43744
	ds_read_b128 v[92:95], v205 offset:52416
	ds_read_b128 v[88:91], v205 offset:52448
	ds_read_b128 v[84:87], v205 offset:61120
	ds_read_b128 v[80:83], v205 offset:61152
	v_pk_add_f32 v[244:245], v[64:65], v[244:245]
	v_pk_add_f32 v[246:247], v[66:67], v[246:247]
	v_pk_add_f32 v[244:245], v[68:69], v[244:245]
	v_pk_add_f32 v[246:247], v[70:71], v[246:247]
	v_cvt_pk_bf16_f32 v64, v64, v65
	v_cvt_pk_bf16_f32 v65, v66, v67
	v_cvt_pk_bf16_f32 v66, v68, v69
	v_cvt_pk_bf16_f32 v67, v70, v71
	v_pk_add_f32 v[244:245], v[72:73], v[244:245]
	v_pk_add_f32 v[246:247], v[74:75], v[246:247]
	s_waitcnt lgkmcnt(7)
	v_mfma_f32_32x32x16_bf16 v[48:63], v[150:153], v[64:67], v[48:63]
	v_add_u32_e32 v206, s1, v202
	s_waitcnt vmcnt(7)
	ds_write_b128 v206, v[114:117]
	s_waitcnt vmcnt(6)
	ds_write_b128 v206, v[118:121] offset:34816
	v_cvt_pk_bf16_f32 v68, v72, v73
	v_cvt_pk_bf16_f32 v69, v74, v75
	v_cvt_pk_bf16_f32 v70, v76, v77
	v_cvt_pk_bf16_f32 v71, v78, v79
	v_pk_add_f32 v[244:245], v[76:77], v[244:245]
	v_pk_add_f32 v[246:247], v[78:79], v[246:247]
	s_waitcnt lgkmcnt(7)
	v_mfma_f32_32x32x16_bf16 v[32:47], v[158:161], v[64:67], v[32:47]
	s_waitcnt vmcnt(5)
	ds_write_b128 v206, v[122:125] offset:8704
	s_waitcnt vmcnt(4)
	ds_write_b128 v206, v[126:129] offset:43520
	s_waitcnt lgkmcnt(7)
	v_mfma_f32_32x32x16_bf16 v[16:31], v[92:95], v[64:67], v[16:31]
	s_waitcnt vmcnt(3)
	ds_write_b128 v206, v[130:133] offset:17408
	s_waitcnt vmcnt(2)
	ds_write_b128 v206, v[134:137] offset:52224
	s_waitcnt lgkmcnt(7)
	v_mfma_f32_32x32x16_bf16 v[0:15], v[84:87], v[64:67], v[0:15]
	s_waitcnt vmcnt(1)
	ds_write_b128 v206, v[138:141] offset:26112
	s_waitcnt vmcnt(0)
	ds_write_b128 v206, v[142:145] offset:60928
	v_mfma_f32_32x32x16_bf16 v[48:63], v[154:157], v[68:71], v[48:63]
	v_mfma_f32_32x32x16_bf16 v[32:47], v[146:149], v[68:71], v[32:47]
	v_mfma_f32_32x32x16_bf16 v[16:31], v[88:91], v[68:71], v[16:31]
	s_waitcnt lgkmcnt(8)
	v_mfma_f32_32x32x16_bf16 v[0:15], v[80:83], v[68:71], v[0:15]
	s_waitcnt lgkmcnt(0)
	s_barrier
	s_cbranch_scc1 .LBB0_604

; DEV void attn_tile(const Params& p, int l, int tile, char* smem, bool do_store = true) {
;     ...
;     const char* kp = Ks + (h2 * 64 + kos) * KROW + (map * 64 + hh * 8) * 2;
;     const char* vp = Vs + ql * KROW + hh * 16 + h2 * 128;
;     bf16x8 kf0[4], kf1[4];
; #pragma unroll
;     for (int ks = 0; ks < 4; ++ks) { kf0[ks] = *(const bf16x8*)(kp + ks * 32); kf1[ks] = *(const bf16x8*)(kp + 32 * KROW + ks * 32); }
;     f32x16 s0, s1;
; #pragma unroll
;     for (int e = 0; e < 16; ++e) { s0[e] = 0.f; s1[e] = 0.f; }
; #pragma unroll
;     for (int ks = 0; ks < 4; ++ks) s0 = __builtin_amdgcn_mfma_f32_32x32x16_bf16(kf0[ks], qf[ks], s0, 0, 0, 0);
; #pragma unroll
;     for (int ks = 0; ks < 4; ++ks) s1 = __builtin_amdgcn_mfma_f32_32x32x16_bf16(kf1[ks], qf[ks], s1, 0, 0, 0);
;     bf16x8 vf[8];
; #pragma unroll
;     for (int dt = 0; dt < 4; ++dt)
; #pragma unroll
;       for (int k2 = 0; k2 < 2; ++k2) vf[dt * 2 + k2] = *(const bf16x8*)(vp + dt * 32 * KROW + (k2 * 16) * 2);
;     float mx = fmaxf(s0[0], s1[0]);
; #pragma unroll
;     for (int e = 1; e < 16; ++e) mx = fmaxf(mx, fmaxf(s0[e], s1[e]));
;     mx = xor32_max(mx);
;     const float mnew = (mx > m + 8.f) ? mx : m;
;     if (__any(mnew > m)) {
;       const float alpha = __builtin_amdgcn_exp2f(m - mnew);
;       lsum *= alpha;
; #pragma unroll
;       for (int dt = 0; dt < 4; ++dt)
; #pragma unroll
;         for (int e = 0; e < 16; ++e) o[dt][e] *= alpha;
;     }
;     m = mnew;
;     bf16x8 pb0[2], pb1[2];
;     {
;       float pe[16];
; #pragma unroll
;       for (int e = 0; e < 16; ++e) { pe[e] = __builtin_amdgcn_exp2f(s0[e] - m); lsum += pe[e]; }
; #pragma unroll
;       for (int k2 = 0; k2 < 2; ++k2) {
;         u32x4 u;
;         u[0] = pk2(pe[8 * k2 + 0], pe[8 * k2 + 1]); u[1] = pk2(pe[8 * k2 + 2], pe[8 * k2 + 3]);
;         u[2] = pk2(pe[8 * k2 + 4], pe[8 * k2 + 5]); u[3] = pk2(pe[8 * k2 + 6], pe[8 * k2 + 7]);
;         pb0[k2] = __builtin_bit_cast(bf16x8, u);
.Latt_a3_qk:
	s_waitcnt lgkmcnt(6)
	v_mfma_f32_32x32x16_bf16 v[80:95], v[68:71], v[110:113], 0
	s_waitcnt lgkmcnt(5)
	v_mfma_f32_32x32x16_bf16 v[80:95], v[72:75], v[106:109], v[80:95]
	s_waitcnt lgkmcnt(3)
	v_mfma_f32_32x32x16_bf16 v[80:95], v[76:79], v[102:105], v[80:95]
	v_mfma_f32_32x32x16_bf16 v[64:79], v[64:67], v[110:113], 0
	v_mfma_f32_32x32x16_bf16 v[64:79], v[212:215], v[106:109], v[64:79]
	s_waitcnt lgkmcnt(2)
	v_mfma_f32_32x32x16_bf16 v[64:79], v[216:219], v[102:105], v[64:79]
	s_waitcnt lgkmcnt(1)
	v_mfma_f32_32x32x16_bf16 v[80:95], v[146:149], v[98:101], v[80:95]
	ds_read_b128 v[174:177], v205 offset:34816
	ds_read_b128 v[170:173], v205 offset:34848
	ds_read_b128 v[166:169], v205 offset:43520
	ds_read_b128 v[162:165], v205 offset:43552
	ds_read_b128 v[146:149], v205 offset:52224
	ds_read_b128 v[150:153], v205 offset:52256
	ds_read_b128 v[154:157], v205 offset:60928
	ds_read_b128 v[158:161], v205 offset:60960
	s_waitcnt lgkmcnt(8)
	v_mfma_f32_32x32x16_bf16 v[64:79], v[178:181], v[98:101], v[64:79]
	s_nop 1
	v_max3_f32 v178, v80, v81, v82
	v_max3_f32 v179, v83, v84, v85
	v_max3_f32 v180, v86, v87, v88
	v_max3_f32 v181, v89, v90, v91
	v_max3_f32 v178, v178, v92, v93
	v_max3_f32 v179, v179, v94, v95
	v_add_f32_e32 v241, 0x41000000, v208
	s_nop 2
	v_max3_f32 v180, v180, v64, v65
	v_max3_f32 v181, v181, v66, v67
	v_max3_f32 v178, v178, v68, v69
	v_max3_f32 v179, v179, v70, v71
	v_max3_f32 v180, v180, v72, v73
	v_max3_f32 v181, v181, v74, v75
	v_max3_f32 v178, v178, v76, v77
	v_max3_f32 v179, v179, v78, v79
	v_max3_f32 v178, v178, v179, v180
	v_max_f32_e32 v178, v178, v181
	v_mov_b32_e32 v179, v178
	s_nop 1
	v_permlane32_swap_b32_e32 v178, v179
	v_max_f32_e32 v178, v178, v179
	v_cmp_gt_f32_e32 vcc, v178, v241
	s_nop 1
	v_cndmask_b32_e32 v211, v208, v178, vcc
	s_cbranch_vccz .LBB0_602
	v_sub_f32_e32 v178, v208, v211
	v_exp_f32_e32 v178, v178
	s_nop 0
	v_pk_mul_f32 v[62:63], v[62:63], v[178:179] op_sel_hi:[1,0]
	v_pk_mul_f32 v[60:61], v[60:61], v[178:179] op_sel_hi:[1,0]
	v_pk_mul_f32 v[58:59], v[58:59], v[178:179] op_sel_hi:[1,0]
	v_pk_mul_f32 v[56:57], v[56:57], v[178:179] op_sel_hi:[1,0]
	v_pk_mul_f32 v[54:55], v[54:55], v[178:179] op_sel_hi:[1,0]
	v_pk_mul_f32 v[52:53], v[52:53], v[178:179] op_sel_hi:[1,0]
	v_pk_mul_f32 v[50:51], v[50:51], v[178:179] op_sel_hi:[1,0]
	v_pk_mul_f32 v[48:49], v[48:49], v[178:179] op_sel_hi:[1,0]
	v_pk_mul_f32 v[46:47], v[46:47], v[178:179] op_sel_hi:[1,0]
	v_pk_mul_f32 v[44:45], v[44:45], v[178:179] op_sel_hi:[1,0]
	v_pk_mul_f32 v[42:43], v[42:43], v[178:179] op_sel_hi:[1,0]
	v_pk_mul_f32 v[40:41], v[40:41], v[178:179] op_sel_hi:[1,0]
	v_pk_mul_f32 v[38:39], v[38:39], v[178:179] op_sel_hi:[1,0]
	v_pk_mul_f32 v[36:37], v[36:37], v[178:179] op_sel_hi:[1,0]
	v_pk_mul_f32 v[34:35], v[34:35], v[178:179] op_sel_hi:[1,0]
	v_pk_mul_f32 v[32:33], v[32:33], v[178:179] op_sel_hi:[1,0]
	v_pk_mul_f32 v[30:31], v[30:31], v[178:179] op_sel_hi:[1,0]
	v_pk_mul_f32 v[28:29], v[28:29], v[178:179] op_sel_hi:[1,0]
	v_pk_mul_f32 v[26:27], v[26:27], v[178:179] op_sel_hi:[1,0]
	v_pk_mul_f32 v[24:25], v[24:25], v[178:179] op_sel_hi:[1,0]
	v_pk_mul_f32 v[22:23], v[22:23], v[178:179] op_sel_hi:[1,0]
	v_pk_mul_f32 v[20:21], v[20:21], v[178:179] op_sel_hi:[1,0]
	v_pk_mul_f32 v[18:19], v[18:19], v[178:179] op_sel_hi:[1,0]
	v_pk_mul_f32 v[16:17], v[16:17], v[178:179] op_sel_hi:[1,0]
	v_pk_mul_f32 v[14:15], v[14:15], v[178:179] op_sel_hi:[1,0]
	v_pk_mul_f32 v[12:13], v[12:13], v[178:179] op_sel_hi:[1,0]
	v_pk_mul_f32 v[10:11], v[10:11], v[178:179] op_sel_hi:[1,0]
	v_pk_mul_f32 v[8:9], v[8:9], v[178:179] op_sel_hi:[1,0]
	v_pk_mul_f32 v[6:7], v[6:7], v[178:179] op_sel_hi:[1,0]
	v_pk_mul_f32 v[4:5], v[4:5], v[178:179] op_sel_hi:[1,0]
	v_pk_mul_f32 v[2:3], v[2:3], v[178:179] op_sel_hi:[1,0]
	v_pk_mul_f32 v[0:1], v[0:1], v[178:179] op_sel_hi:[1,0]
	v_mul_f32_e32 v209, v209, v178
	v_pk_mul_f32 v[244:245], v[244:245], v[178:179] op_sel_hi:[1,0]
	v_pk_mul_f32 v[246:247], v[246:247], v[178:179] op_sel_hi:[1,0]
.LBB0_602:
	v_pk_add_f32 v[80:81], v[80:81], v[210:211] op_sel:[0,1] op_sel_hi:[1,1] neg_lo:[0,1] neg_hi:[0,1]
	v_pk_add_f32 v[82:83], v[82:83], v[210:211] op_sel:[0,1] op_sel_hi:[1,1] neg_lo:[0,1] neg_hi:[0,1]
	v_pk_add_f32 v[84:85], v[84:85], v[210:211] op_sel:[0,1] op_sel_hi:[1,1] neg_lo:[0,1] neg_hi:[0,1]
	v_pk_add_f32 v[86:87], v[86:87], v[210:211] op_sel:[0,1] op_sel_hi:[1,1] neg_lo:[0,1] neg_hi:[0,1]
	v_pk_add_f32 v[88:89], v[88:89], v[210:211] op_sel:[0,1] op_sel_hi:[1,1] neg_lo:[0,1] neg_hi:[0,1]
	v_pk_add_f32 v[90:91], v[90:91], v[210:211] op_sel:[0,1] op_sel_hi:[1,1] neg_lo:[0,1] neg_hi:[0,1]
	v_pk_add_f32 v[92:93], v[92:93], v[210:211] op_sel:[0,1] op_sel_hi:[1,1] neg_lo:[0,1] neg_hi:[0,1]
	v_pk_add_f32 v[94:95], v[94:95], v[210:211] op_sel:[0,1] op_sel_hi:[1,1] neg_lo:[0,1] neg_hi:[0,1]
	v_exp_f32_e32 v80, v80
	v_exp_f32_e32 v81, v81
	v_exp_f32_e32 v82, v82
	v_exp_f32_e32 v83, v83
	v_exp_f32_e32 v84, v84
	v_exp_f32_e32 v85, v85
	v_exp_f32_e32 v86, v86
	v_exp_f32_e32 v87, v87
	v_exp_f32_e32 v88, v88
	v_exp_f32_e32 v89, v89
	v_exp_f32_e32 v90, v90
	v_exp_f32_e32 v91, v91
	v_exp_f32_e32 v92, v92
	v_exp_f32_e32 v93, v93
	v_exp_f32_e32 v94, v94
	v_exp_f32_e32 v95, v95
	v_pk_add_f32 v[244:245], v[80:81], v[244:245]
	v_pk_add_f32 v[246:247], v[82:83], v[246:247]
	v_cvt_pk_bf16_f32 v80, v80, v81
	v_cvt_pk_bf16_f32 v81, v82, v83
	v_cvt_pk_bf16_f32 v82, v84, v85
	v_cvt_pk_bf16_f32 v83, v86, v87
	v_pk_add_f32 v[244:245], v[84:85], v[244:245]
	v_pk_add_f32 v[246:247], v[86:87], v[246:247]
	s_waitcnt lgkmcnt(5)
; DEV void attn_tile(const Params& p, int l, int tile, char* smem, bool do_store = true) {
;     ...
;     const char* kp = Ks + (h2 * 64 + kos) * KROW + (map * 64 + hh * 8) * 2;
;     const char* vp = Vs + ql * KROW + hh * 16 + h2 * 128;
;     bf16x8 kf0[4], kf1[4];
; #pragma unroll
;     for (int ks = 0; ks < 4; ++ks) { kf0[ks] = *(const bf16x8*)(kp + ks * 32); kf1[ks] = *(const bf16x8*)(kp + 32 * KROW + ks * 32); }
;     f32x16 s0, s1;
; #pragma unroll
;     for (int e = 0; e < 16; ++e) { s0[e] = 0.f; s1[e] = 0.f; }
; #pragma unroll
;     for (int ks = 0; ks < 4; ++ks) s0 = __builtin_amdgcn_mfma_f32_32x32x16_bf16(kf0[ks], qf[ks], s0, 0, 0, 0);
; #pragma unroll
;     for (int ks = 0; ks < 4; ++ks) s1 = __builtin_amdgcn_mfma_f32_32x32x16_bf16(kf1[ks], qf[ks], s1, 0, 0, 0);
;     bf16x8 vf[8];
;     ...
;     bf16x8 pb0[2], pb1[2];
;     {
;       float pe[16];
; #pragma unroll
;       for (int e = 0; e < 16; ++e) { pe[e] = __builtin_amdgcn_exp2f(s0[e] - m); lsum += pe[e]; }
; #pragma unroll
;       for (int k2 = 0; k2 < 2; ++k2) {
;         u32x4 u;
;         u[0] = pk2(pe[8 * k2 + 0], pe[8 * k2 + 1]); u[1] = pk2(pe[8 * k2 + 2], pe[8 * k2 + 3]);
;         u[2] = pk2(pe[8 * k2 + 4], pe[8 * k2 + 5]); u[3] = pk2(pe[8 * k2 + 6], pe[8 * k2 + 7]);
;         pb0[k2] = __builtin_bit_cast(bf16x8, u);
;       }
;     }
; #pragma unroll
;     for (int dt = 0; dt < 4; ++dt)
; #pragma unroll
;       for (int k2 = 0; k2 < 2; ++k2) o[dt] = __builtin_amdgcn_mfma_f32_32x32x16_bf16(vf[dt * 2 + k2], pb0[k2], o[dt], 0, 0, 0);
; #pragma unroll
;     for (int dt = 0; dt < 4; ++dt)
; #pragma unroll
;       for (int k2 = 0; k2 < 2; ++k2) vf[dt * 2 + k2] = *(const bf16x8*)(vp + dt * 32 * KROW + (32 + k2 * 16) * 2);
;     {
;       float pe[16];
; #pragma unroll
;       for (int e = 0; e < 16; ++e) { pe[e] = __builtin_amdgcn_exp2f(s1[e] - m); lsum += pe[e]; }
; #pragma unroll
;       for (int k2 = 0; k2 < 2; ++k2) {
;         u32x4 u;
;         u[0] = pk2(pe[8 * k2 + 0], pe[8 * k2 + 1]); u[1] = pk2(pe[8 * k2 + 2], pe[8 * k2 + 3]);
;         u[2] = pk2(pe[8 * k2 + 4], pe[8 * k2 + 5]); u[3] = pk2(pe[8 * k2 + 6], pe[8 * k2 + 7]);
;         pb1[k2] = __builtin_bit_cast(bf16x8, u);
;       }
;     }
; #pragma unroll
;     for (int dt = 0; dt < 4; ++dt)
; #pragma unroll
;       for (int k2 = 0; k2 < 2; ++k2) o[dt] = __builtin_amdgcn_mfma_f32_32x32x16_bf16(vf[dt * 2 + k2], pb1[k2], o[dt], 0, 0, 0);
	v_mfma_f32_32x32x16_bf16 v[32:47], v[166:169], v[80:83], v[32:47]
	v_cvt_pk_bf16_f32 v84, v88, v89
	v_cvt_pk_bf16_f32 v85, v90, v91
	v_cvt_pk_bf16_f32 v86, v92, v93
	v_cvt_pk_bf16_f32 v87, v94, v95
	v_pk_add_f32 v[244:245], v[88:89], v[244:245]
	v_pk_add_f32 v[246:247], v[90:91], v[246:247]
	v_mfma_f32_32x32x16_bf16 v[48:63], v[174:177], v[80:83], v[48:63]
	v_pk_add_f32 v[244:245], v[92:93], v[244:245]
	v_pk_add_f32 v[246:247], v[94:95], v[246:247]
	v_pk_add_f32 v[64:65], v[64:65], v[210:211] op_sel:[0,1] op_sel_hi:[1,1] neg_lo:[0,1] neg_hi:[0,1]
	v_pk_add_f32 v[66:67], v[66:67], v[210:211] op_sel:[0,1] op_sel_hi:[1,1] neg_lo:[0,1] neg_hi:[0,1]
	v_pk_add_f32 v[68:69], v[68:69], v[210:211] op_sel:[0,1] op_sel_hi:[1,1] neg_lo:[0,1] neg_hi:[0,1]
	v_pk_add_f32 v[70:71], v[70:71], v[210:211] op_sel:[0,1] op_sel_hi:[1,1] neg_lo:[0,1] neg_hi:[0,1]
	s_waitcnt lgkmcnt(4)
	v_mfma_f32_32x32x16_bf16 v[32:47], v[162:165], v[84:87], v[32:47]
	v_pk_add_f32 v[72:73], v[72:73], v[210:211] op_sel:[0,1] op_sel_hi:[1,1] neg_lo:[0,1] neg_hi:[0,1]
	v_pk_add_f32 v[74:75], v[74:75], v[210:211] op_sel:[0,1] op_sel_hi:[1,1] neg_lo:[0,1] neg_hi:[0,1]
	v_pk_add_f32 v[76:77], v[76:77], v[210:211] op_sel:[0,1] op_sel_hi:[1,1] neg_lo:[0,1] neg_hi:[0,1]
	v_pk_add_f32 v[78:79], v[78:79], v[210:211] op_sel:[0,1] op_sel_hi:[1,1] neg_lo:[0,1] neg_hi:[0,1]
	v_exp_f32_e32 v64, v64
	v_exp_f32_e32 v65, v65
	v_exp_f32_e32 v66, v66
	v_exp_f32_e32 v67, v67
	s_waitcnt lgkmcnt(3)
	v_mfma_f32_32x32x16_bf16 v[16:31], v[146:149], v[80:83], v[16:31]
	v_exp_f32_e32 v68, v68
	v_exp_f32_e32 v69, v69
	v_exp_f32_e32 v70, v70
	v_exp_f32_e32 v71, v71
	s_waitcnt lgkmcnt(1)
	v_mfma_f32_32x32x16_bf16 v[0:15], v[154:157], v[80:83], v[0:15]
	v_exp_f32_e32 v72, v72
	v_exp_f32_e32 v73, v73
	v_exp_f32_e32 v74, v74
	v_exp_f32_e32 v75, v75
	v_mfma_f32_32x32x16_bf16 v[48:63], v[170:173], v[84:87], v[48:63]
	v_exp_f32_e32 v76, v76
	v_exp_f32_e32 v77, v77
	v_exp_f32_e32 v78, v78
	v_exp_f32_e32 v79, v79
	v_mfma_f32_32x32x16_bf16 v[16:31], v[150:153], v[84:87], v[16:31]
	v_pk_add_f32 v[244:245], v[64:65], v[244:245]
	v_pk_add_f32 v[246:247], v[66:67], v[246:247]
	v_pk_add_f32 v[244:245], v[68:69], v[244:245]
	v_pk_add_f32 v[246:247], v[70:71], v[246:247]
	s_waitcnt lgkmcnt(0)
	v_mfma_f32_32x32x16_bf16 v[0:15], v[158:161], v[84:87], v[0:15]
	ds_read_b128 v[80:83], v205 offset:34880
	ds_read_b128 v[84:87], v205 offset:34912
	ds_read_b128 v[88:91], v205 offset:43584
	ds_read_b128 v[92:95], v205 offset:43616
	ds_read_b128 v[146:149], v205 offset:52288
	ds_read_b128 v[150:153], v205 offset:52320
	ds_read_b128 v[154:157], v205 offset:60992
	ds_read_b128 v[158:161], v205 offset:61024
	v_cvt_pk_bf16_f32 v64, v64, v65
	v_cvt_pk_bf16_f32 v65, v66, v67
	v_cvt_pk_bf16_f32 v66, v68, v69
	v_cvt_pk_bf16_f32 v67, v70, v71
	v_pk_add_f32 v[244:245], v[72:73], v[244:245]
	v_pk_add_f32 v[246:247], v[74:75], v[246:247]
	s_waitcnt lgkmcnt(7)
	v_mfma_f32_32x32x16_bf16 v[48:63], v[80:83], v[64:67], v[48:63]
	v_cvt_pk_bf16_f32 v68, v72, v73
	v_cvt_pk_bf16_f32 v69, v74, v75
	v_cvt_pk_bf16_f32 v70, v76, v77
	v_cvt_pk_bf16_f32 v71, v78, v79
	v_pk_add_f32 v[244:245], v[76:77], v[244:245]
	v_pk_add_f32 v[246:247], v[78:79], v[246:247]
	s_waitcnt lgkmcnt(5)
	v_mfma_f32_32x32x16_bf16 v[32:47], v[88:91], v[64:67], v[32:47]
	s_waitcnt lgkmcnt(3)
	v_mfma_f32_32x32x16_bf16 v[16:31], v[146:149], v[64:67], v[16:31]
	s_waitcnt lgkmcnt(1)
	v_mfma_f32_32x32x16_bf16 v[0:15], v[154:157], v[64:67], v[0:15]
	v_mfma_f32_32x32x16_bf16 v[48:63], v[84:87], v[68:71], v[48:63]
	v_mfma_f32_32x32x16_bf16 v[32:47], v[92:95], v[68:71], v[32:47]
	v_mfma_f32_32x32x16_bf16 v[16:31], v[150:153], v[68:71], v[16:31]
	s_waitcnt lgkmcnt(0)
	v_mfma_f32_32x32x16_bf16 v[0:15], v[158:161], v[68:71], v[0:15]
	ds_read_b128 v[64:67], v210 offset:26112
	ds_read_b128 v[68:71], v210 offset:17408
	ds_read_b128 v[72:75], v210 offset:17440
	ds_read_b128 v[212:215], v210 offset:26144
	ds_read_b128 v[76:79], v210 offset:17472
	ds_read_b128 v[216:219], v210 offset:26176
	ds_read_b128 v[146:149], v210 offset:17504
	ds_read_b128 v[178:181], v210 offset:26208
	s_waitcnt lgkmcnt(6)
	v_mfma_f32_32x32x16_bf16 v[80:95], v[68:71], v[110:113], 0
	s_waitcnt lgkmcnt(5)
	v_mfma_f32_32x32x16_bf16 v[80:95], v[72:75], v[106:109], v[80:95]
	s_waitcnt lgkmcnt(3)
	v_mfma_f32_32x32x16_bf16 v[80:95], v[76:79], v[102:105], v[80:95]
	v_mfma_f32_32x32x16_bf16 v[64:79], v[64:67], v[110:113], 0
	v_mfma_f32_32x32x16_bf16 v[64:79], v[212:215], v[106:109], v[64:79]
	s_waitcnt lgkmcnt(2)
	v_mfma_f32_32x32x16_bf16 v[64:79], v[216:219], v[102:105], v[64:79]
	s_waitcnt lgkmcnt(1)
	v_mfma_f32_32x32x16_bf16 v[80:95], v[146:149], v[98:101], v[80:95]
	ds_read_b128 v[174:177], v205 offset:34944
	ds_read_b128 v[170:173], v205 offset:34976
	ds_read_b128 v[166:169], v205 offset:43648
	ds_read_b128 v[162:165], v205 offset:43680
	ds_read_b128 v[146:149], v205 offset:52352
	ds_read_b128 v[150:153], v205 offset:52384
	ds_read_b128 v[154:157], v205 offset:61056
	ds_read_b128 v[158:161], v205 offset:61088
	s_waitcnt lgkmcnt(8)
	v_mfma_f32_32x32x16_bf16 v[64:79], v[178:181], v[98:101], v[64:79]
	s_nop 1
	v_max3_f32 v178, v80, v81, v82
	v_max3_f32 v179, v83, v84, v85
	v_max3_f32 v180, v86, v87, v88
	v_max3_f32 v181, v89, v90, v91
	v_max3_f32 v178, v178, v92, v93
	v_max3_f32 v179, v179, v94, v95
	v_add_f32_e32 v241, 0x41000000, v211
	s_nop 2
	v_max3_f32 v180, v180, v64, v65
	v_max3_f32 v181, v181, v66, v67
	v_max3_f32 v178, v178, v68, v69
	v_max3_f32 v179, v179, v70, v71
	v_max3_f32 v180, v180, v72, v73
	v_max3_f32 v181, v181, v74, v75
	v_max3_f32 v178, v178, v76, v77
	v_max3_f32 v179, v179, v78, v79
	v_max3_f32 v178, v178, v179, v180
	v_max_f32_e32 v178, v178, v181
	v_mov_b32_e32 v179, v178
	s_nop 1
	v_permlane32_swap_b32_e32 v178, v179
	v_max_f32_e32 v178, v178, v179
	v_cmp_gt_f32_e32 vcc, v178, v241
	s_nop 1
	v_cndmask_b32_e32 v208, v211, v178, vcc
	s_cbranch_vccz .LBB0_599
; DEV void attn_tile(const Params& p, int l, int tile, char* smem, bool do_store = true) {
;     ...
;     if (__any(mnew > m)) {
;       const float alpha = __builtin_amdgcn_exp2f(m - mnew);
;       lsum *= alpha;
; #pragma unroll
;       for (int dt = 0; dt < 4; ++dt)
; #pragma unroll
;         for (int e = 0; e < 16; ++e) o[dt][e] *= alpha;
;     }
	v_sub_f32_e32 v178, v211, v208
	v_exp_f32_e32 v178, v178
	s_nop 0
	v_pk_mul_f32 v[62:63], v[62:63], v[178:179] op_sel_hi:[1,0]
	v_pk_mul_f32 v[60:61], v[60:61], v[178:179] op_sel_hi:[1,0]
	v_pk_mul_f32 v[58:59], v[58:59], v[178:179] op_sel_hi:[1,0]
	v_pk_mul_f32 v[56:57], v[56:57], v[178:179] op_sel_hi:[1,0]
	v_pk_mul_f32 v[54:55], v[54:55], v[178:179] op_sel_hi:[1,0]
	v_pk_mul_f32 v[52:53], v[52:53], v[178:179] op_sel_hi:[1,0]
	v_pk_mul_f32 v[50:51], v[50:51], v[178:179] op_sel_hi:[1,0]
	v_pk_mul_f32 v[48:49], v[48:49], v[178:179] op_sel_hi:[1,0]
	v_pk_mul_f32 v[46:47], v[46:47], v[178:179] op_sel_hi:[1,0]
	v_pk_mul_f32 v[44:45], v[44:45], v[178:179] op_sel_hi:[1,0]
	v_pk_mul_f32 v[42:43], v[42:43], v[178:179] op_sel_hi:[1,0]
	v_pk_mul_f32 v[40:41], v[40:41], v[178:179] op_sel_hi:[1,0]
	v_pk_mul_f32 v[38:39], v[38:39], v[178:179] op_sel_hi:[1,0]
	v_pk_mul_f32 v[36:37], v[36:37], v[178:179] op_sel_hi:[1,0]
	v_pk_mul_f32 v[34:35], v[34:35], v[178:179] op_sel_hi:[1,0]
	v_pk_mul_f32 v[32:33], v[32:33], v[178:179] op_sel_hi:[1,0]
	v_pk_mul_f32 v[30:31], v[30:31], v[178:179] op_sel_hi:[1,0]
	v_pk_mul_f32 v[28:29], v[28:29], v[178:179] op_sel_hi:[1,0]
	v_pk_mul_f32 v[26:27], v[26:27], v[178:179] op_sel_hi:[1,0]
	v_pk_mul_f32 v[24:25], v[24:25], v[178:179] op_sel_hi:[1,0]
	v_pk_mul_f32 v[22:23], v[22:23], v[178:179] op_sel_hi:[1,0]
	v_pk_mul_f32 v[20:21], v[20:21], v[178:179] op_sel_hi:[1,0]
	v_pk_mul_f32 v[18:19], v[18:19], v[178:179] op_sel_hi:[1,0]
	v_pk_mul_f32 v[16:17], v[16:17], v[178:179] op_sel_hi:[1,0]
	v_pk_mul_f32 v[14:15], v[14:15], v[178:179] op_sel_hi:[1,0]
	v_pk_mul_f32 v[12:13], v[12:13], v[178:179] op_sel_hi:[1,0]
	v_pk_mul_f32 v[10:11], v[10:11], v[178:179] op_sel_hi:[1,0]
	v_pk_mul_f32 v[8:9], v[8:9], v[178:179] op_sel_hi:[1,0]
	v_pk_mul_f32 v[6:7], v[6:7], v[178:179] op_sel_hi:[1,0]
	v_pk_mul_f32 v[4:5], v[4:5], v[178:179] op_sel_hi:[1,0]
	v_pk_mul_f32 v[2:3], v[2:3], v[178:179] op_sel_hi:[1,0]
	v_pk_mul_f32 v[0:1], v[0:1], v[178:179] op_sel_hi:[1,0]
	v_mul_f32_e32 v209, v209, v178
	v_pk_mul_f32 v[244:245], v[244:245], v[178:179] op_sel_hi:[1,0]
	v_pk_mul_f32 v[246:247], v[246:247], v[178:179] op_sel_hi:[1,0]
	s_branch .LBB0_599
; DEV void attn_tile(const Params& p, int l, int tile, char* smem, bool do_store = true) {
;     ...
;     const char* kp = Ks + (h2 * 64 + kos) * KROW + (map * 64 + hh * 8) * 2;
;     const char* vp = Vs + ql * KROW + hh * 16 + h2 * 128;
;     bf16x8 kf0[4], kf1[4];
; #pragma unroll
;     for (int ks = 0; ks < 4; ++ks) { kf0[ks] = *(const bf16x8*)(kp + ks * 32); kf1[ks] = *(const bf16x8*)(kp + 32 * KROW + ks * 32); }
;     f32x16 s0, s1;
; #pragma unroll
;     for (int e = 0; e < 16; ++e) { s0[e] = 0.f; s1[e] = 0.f; }
; #pragma unroll
;     for (int ks = 0; ks < 4; ++ks) s0 = __builtin_amdgcn_mfma_f32_32x32x16_bf16(kf0[ks], qf[ks], s0, 0, 0, 0);
; #pragma unroll
;     for (int ks = 0; ks < 4; ++ks) s1 = __builtin_amdgcn_mfma_f32_32x32x16_bf16(kf1[ks], qf[ks], s1, 0, 0, 0);
;     bf16x8 vf[8];
; #pragma unroll
;     for (int dt = 0; dt < 4; ++dt)
; #pragma unroll
;       for (int k2 = 0; k2 < 2; ++k2) vf[dt * 2 + k2] = *(const bf16x8*)(vp + dt * 32 * KROW + (k2 * 16) * 2);
;     float mx = fmaxf(s0[0], s1[0]);
; #pragma unroll
;     for (int e = 1; e < 16; ++e) mx = fmaxf(mx, fmaxf(s0[e], s1[e]));
;     mx = xor32_max(mx);
;     const float mnew = (mx > m + 8.f) ? mx : m;
;     if (__any(mnew > m)) {
;       const float alpha = __builtin_amdgcn_exp2f(m - mnew);
;       lsum *= alpha;
; #pragma unroll
;       for (int dt = 0; dt < 4; ++dt)
; #pragma unroll
;         for (int e = 0; e < 16; ++e) o[dt][e] *= alpha;
;     }
.LBB0_604:
	v_pk_add_f32 v[244:245], v[244:245], v[246:247]
	s_nop 0
	v_add_f32_e32 v244, v244, v245
	s_nop 0
	v_add_f32_e32 v209, v209, v244
	s_bitcmp1_b32 s0, 0
	s_cselect_b32 s0, 0x11000, 0
	s_add_i32 s0, s0, 0
	v_add_u32_e32 v64, s0, v204
	v_add_u32_e32 v147, v64, v203
	ds_read_b128 v[64:67], v147
	ds_read_b128 v[68:71], v147 offset:32
	s_waitcnt lgkmcnt(1)
	v_mfma_f32_32x32x16_bf16 v[80:95], v[64:67], v[110:113], 0
	ds_read_b128 v[64:67], v147 offset:64
	ds_read_b128 v[148:151], v147 offset:96
	s_waitcnt lgkmcnt(2)
	v_mfma_f32_32x32x16_bf16 v[80:95], v[68:71], v[106:109], v[80:95]
	s_waitcnt lgkmcnt(1)
	v_mfma_f32_32x32x16_bf16 v[80:95], v[64:67], v[102:105], v[80:95]
	ds_read_b128 v[64:67], v147 offset:8704
	ds_read_b128 v[114:117], v147 offset:8736
	s_waitcnt lgkmcnt(1)
	v_mfma_f32_32x32x16_bf16 v[64:79], v[64:67], v[110:113], 0
	s_waitcnt lgkmcnt(0)
	v_mfma_f32_32x32x16_bf16 v[64:79], v[114:117], v[106:109], v[64:79]
	ds_read_b128 v[114:117], v147 offset:8768
	ds_read_b128 v[118:121], v147 offset:8800
	s_waitcnt lgkmcnt(1)
	v_mfma_f32_32x32x16_bf16 v[64:79], v[114:117], v[102:105], v[64:79]
	v_add_u32_e32 v114, s0, v201
	v_add_u32_e32 v146, v114, v96
	ds_read_b128 v[142:145], v146 offset:34816
	ds_read_b128 v[130:133], v146 offset:34848
	s_waitcnt lgkmcnt(2)
	v_mfma_f32_32x32x16_bf16 v[64:79], v[118:121], v[98:101], v[64:79]
	ds_read_b128 v[138:141], v146 offset:43520
	ds_read_b128 v[134:137], v146 offset:43552
	ds_read_b128 v[122:125], v146 offset:52224
	ds_read_b128 v[126:129], v146 offset:52256
	ds_read_b128 v[118:121], v146 offset:60928
	ds_read_b128 v[114:117], v146 offset:60960
	s_nop 5
	v_max_f32_e32 v152, v65, v65
	v_mfma_f32_32x32x16_bf16 v[80:95], v[148:151], v[98:101], v[80:95]
	v_max_f32_e32 v149, v66, v66
	s_nop 10
	v_max_f32_e32 v148, v81, v81
	v_max_f32_e32 v150, v82, v82
	v_max_f32_e32 v148, v148, v152
	v_max_f32_e32 v149, v150, v149
	v_max_f32_e32 v150, v67, v67
	v_max_f32_e32 v151, v83, v83
	v_max3_f32 v148, v80, v64, v148
	v_max_f32_e32 v150, v151, v150
	v_max3_f32 v148, v148, v149, v150
	v_max_f32_e32 v149, v68, v68
	v_max_f32_e32 v150, v84, v84
	v_max_f32_e32 v149, v150, v149
	v_max_f32_e32 v150, v69, v69
	v_max_f32_e32 v151, v85, v85
	v_max_f32_e32 v150, v151, v150
	v_max3_f32 v148, v148, v149, v150
	v_max_f32_e32 v149, v70, v70
	v_max_f32_e32 v150, v86, v86
	v_max_f32_e32 v149, v150, v149
	v_max_f32_e32 v150, v71, v71
	v_max_f32_e32 v151, v87, v87
	v_max_f32_e32 v150, v151, v150
	v_max3_f32 v148, v148, v149, v150
	v_max_f32_e32 v149, v72, v72
	v_max_f32_e32 v150, v88, v88
	v_max_f32_e32 v149, v150, v149
	v_max_f32_e32 v150, v73, v73
	v_max_f32_e32 v151, v89, v89
	v_max_f32_e32 v150, v151, v150
	v_max3_f32 v148, v148, v149, v150
	v_max_f32_e32 v149, v74, v74
	v_max_f32_e32 v150, v90, v90
	v_max_f32_e32 v149, v150, v149
	v_max_f32_e32 v150, v75, v75
	v_max_f32_e32 v151, v91, v91
	v_max_f32_e32 v150, v151, v150
	v_max3_f32 v148, v148, v149, v150
	v_max_f32_e32 v149, v76, v76
	v_max_f32_e32 v150, v92, v92
	v_max_f32_e32 v149, v150, v149
	v_max_f32_e32 v150, v77, v77
	v_max_f32_e32 v151, v93, v93
	v_max_f32_e32 v150, v151, v150
	v_max3_f32 v148, v148, v149, v150
	v_max_f32_e32 v149, v78, v78
	v_max_f32_e32 v150, v94, v94
	v_max_f32_e32 v149, v150, v149
	v_max_f32_e32 v150, v79, v79
	v_max_f32_e32 v151, v95, v95
	v_max_f32_e32 v150, v151, v150
	v_max3_f32 v148, v148, v149, v150
	v_mov_b32_e32 v149, v148
	s_nop 1
	v_permlane32_swap_b32_e32 v148, v149
	v_max_f32_e32 v149, v149, v149
	v_max_f32_e32 v148, v148, v148
	v_max_f32_e32 v148, v148, v149
	v_add_f32_e32 v149, 0x41000000, v208
	v_cmp_gt_f32_e32 vcc, v148, v149
	s_nop 1
	v_cndmask_b32_e32 v148, v208, v148, vcc
	v_cmp_gt_f32_e32 vcc, v148, v208
	s_cbranch_vccz .LBB0_606
	v_sub_f32_e32 v149, v208, v148
	v_exp_f32_e32 v150, v149
	s_nop 0
	v_pk_mul_f32 v[62:63], v[62:63], v[150:151] op_sel_hi:[1,0]
	v_pk_mul_f32 v[60:61], v[60:61], v[150:151] op_sel_hi:[1,0]
	v_pk_mul_f32 v[58:59], v[58:59], v[150:151] op_sel_hi:[1,0]
	v_pk_mul_f32 v[56:57], v[56:57], v[150:151] op_sel_hi:[1,0]
	v_pk_mul_f32 v[54:55], v[54:55], v[150:151] op_sel_hi:[1,0]
	v_pk_mul_f32 v[52:53], v[52:53], v[150:151] op_sel_hi:[1,0]
	v_pk_mul_f32 v[50:51], v[50:51], v[150:151] op_sel_hi:[1,0]
	v_pk_mul_f32 v[48:49], v[48:49], v[150:151] op_sel_hi:[1,0]
	v_pk_mul_f32 v[46:47], v[46:47], v[150:151] op_sel_hi:[1,0]
	v_pk_mul_f32 v[44:45], v[44:45], v[150:151] op_sel_hi:[1,0]
	v_pk_mul_f32 v[42:43], v[42:43], v[150:151] op_sel_hi:[1,0]
	v_pk_mul_f32 v[40:41], v[40:41], v[150:151] op_sel_hi:[1,0]
	v_pk_mul_f32 v[38:39], v[38:39], v[150:151] op_sel_hi:[1,0]
	v_pk_mul_f32 v[36:37], v[36:37], v[150:151] op_sel_hi:[1,0]
	v_pk_mul_f32 v[34:35], v[34:35], v[150:151] op_sel_hi:[1,0]
	v_pk_mul_f32 v[32:33], v[32:33], v[150:151] op_sel_hi:[1,0]
	v_pk_mul_f32 v[30:31], v[30:31], v[150:151] op_sel_hi:[1,0]
	v_pk_mul_f32 v[28:29], v[28:29], v[150:151] op_sel_hi:[1,0]
	v_pk_mul_f32 v[26:27], v[26:27], v[150:151] op_sel_hi:[1,0]
	v_pk_mul_f32 v[24:25], v[24:25], v[150:151] op_sel_hi:[1,0]
	v_pk_mul_f32 v[22:23], v[22:23], v[150:151] op_sel_hi:[1,0]
	v_pk_mul_f32 v[20:21], v[20:21], v[150:151] op_sel_hi:[1,0]
	v_pk_mul_f32 v[18:19], v[18:19], v[150:151] op_sel_hi:[1,0]
	v_pk_mul_f32 v[16:17], v[16:17], v[150:151] op_sel_hi:[1,0]
	v_pk_mul_f32 v[14:15], v[14:15], v[150:151] op_sel_hi:[1,0]
	v_pk_mul_f32 v[12:13], v[12:13], v[150:151] op_sel_hi:[1,0]
	v_pk_mul_f32 v[10:11], v[10:11], v[150:151] op_sel_hi:[1,0]
	v_pk_mul_f32 v[8:9], v[8:9], v[150:151] op_sel_hi:[1,0]
	v_pk_mul_f32 v[6:7], v[6:7], v[150:151] op_sel_hi:[1,0]
	v_pk_mul_f32 v[4:5], v[4:5], v[150:151] op_sel_hi:[1,0]
	v_pk_mul_f32 v[2:3], v[2:3], v[150:151] op_sel_hi:[1,0]
	v_pk_mul_f32 v[0:1], v[0:1], v[150:151] op_sel_hi:[1,0]
	v_mul_f32_e32 v209, v209, v150
